# G1 and G4 256x128 GEMM mainloops: LDS-DMA issues spread one per MFMA group (addresses precomputed), on top of A-fragment read pipelining
# speedup vs baseline: 1.7462x; 1.0010x over previous
.LBB1_56:
	s_mul_i32 s12, s10, 0x6000
	s_add_i32 s13, s12, 0xffffa000
	s_cmp_lg_u32 s10, 0
	s_cselect_b32 s13, s13, 0xc000
	s_min_u32 s14, s11, 29
	s_lshl_b32 s96, s14, 6
	s_add_i32 s13, s13, 16
	v_lshl_add_u64 v[140:141], v[130:131], 0, s[96:97]
	s_add_i32 s14, s13, s8
	v_lshl_add_u64 v[196:197], v[140:141], 0, s[62:63]
	v_lshl_add_u64 v[198:199], v[140:141], 0, s[60:61]
	v_lshl_add_u64 v[200:201], v[140:141], 0, s[16:17]
	v_lshl_add_u64 v[202:203], v[140:141], 0, s[24:25]
	s_add_i32 s13, s13, s9
	s_add_i32 s12, s12, 16
	v_lshl_add_u64 v[140:141], v[132:133], 0, s[96:97]
	v_lshl_add_u64 v[204:205], v[140:141], 0, s[62:63]
	v_lshl_add_u64 v[206:207], v[140:141], 0, s[60:61]
	s_waitcnt vmcnt(6)
	s_barrier
	v_add3_u32 v152, s12, v139, v138
	ds_read_b128 v[140:143], v152 offset:16384
	ds_read_b128 v[144:147], v152 offset:17408
	ds_read_b128 v[148:151], v152 offset:18432
	ds_read_b128 v[152:155], v152 offset:19456
	s_setprio 1
	v_add3_u32 v160, s12, v137, v138
	ds_read_b128 v[156:159], v160
	ds_read_b128 v[188:191], v160 offset:1024
	ds_read_b128 v[192:195], v160 offset:2048
	s_waitcnt lgkmcnt(2)
	s_mov_b32 m0, s14
	v_mfma_f32_16x16x32_bf16 v[124:127], v[140:143], v[156:159], v[124:127]
	v_mfma_f32_16x16x32_bf16 v[120:123], v[144:147], v[156:159], v[120:123]
	v_mfma_f32_16x16x32_bf16 v[116:119], v[148:151], v[156:159], v[116:119]
	v_mfma_f32_16x16x32_bf16 v[112:115], v[152:155], v[156:159], v[112:115]
	ds_read_b128 v[156:159], v160 offset:3072
	global_load_lds_dwordx4 v[196:197], off
	s_waitcnt lgkmcnt(2)
	s_add_i32 m0, s14, 0x400
	v_mfma_f32_16x16x32_bf16 v[108:111], v[140:143], v[188:191], v[108:111]
	v_mfma_f32_16x16x32_bf16 v[104:107], v[144:147], v[188:191], v[104:107]
	v_mfma_f32_16x16x32_bf16 v[100:103], v[148:151], v[188:191], v[100:103]
	v_mfma_f32_16x16x32_bf16 v[96:99], v[152:155], v[188:191], v[96:99]
	ds_read_b128 v[188:191], v160 offset:4096
	global_load_lds_dwordx4 v[198:199], off
	s_waitcnt lgkmcnt(2)
	s_add_i32 m0, s14, 0x800
	v_mfma_f32_16x16x32_bf16 v[84:87], v[140:143], v[192:195], v[84:87]
	v_mfma_f32_16x16x32_bf16 v[72:75], v[144:147], v[192:195], v[72:75]
	v_mfma_f32_16x16x32_bf16 v[68:71], v[148:151], v[192:195], v[68:71]
	v_mfma_f32_16x16x32_bf16 v[64:67], v[152:155], v[192:195], v[64:67]
	ds_read_b128 v[192:195], v160 offset:5120
	global_load_lds_dwordx4 v[200:201], off
	s_waitcnt lgkmcnt(2)
	s_add_i32 m0, s14, 0xc00
	v_mfma_f32_16x16x32_bf16 v[60:63], v[140:143], v[156:159], v[60:63]
	v_mfma_f32_16x16x32_bf16 v[56:59], v[144:147], v[156:159], v[56:59]
	v_mfma_f32_16x16x32_bf16 v[52:55], v[148:151], v[156:159], v[52:55]
	v_mfma_f32_16x16x32_bf16 v[48:51], v[152:155], v[156:159], v[48:51]
	ds_read_b128 v[156:159], v160 offset:6144
	global_load_lds_dwordx4 v[202:203], off
	s_waitcnt lgkmcnt(2)
	s_add_i32 m0, s13, 0x4000
	v_mfma_f32_16x16x32_bf16 v[44:47], v[140:143], v[188:191], v[44:47]
	v_mfma_f32_16x16x32_bf16 v[40:43], v[144:147], v[188:191], v[40:43]
	v_mfma_f32_16x16x32_bf16 v[36:39], v[148:151], v[188:191], v[36:39]
	v_mfma_f32_16x16x32_bf16 v[32:35], v[152:155], v[188:191], v[32:35]
	ds_read_b128 v[188:191], v160 offset:7168
	global_load_lds_dwordx4 v[204:205], off
	s_waitcnt lgkmcnt(2)
	s_add_i32 m0, s13, 0x4400
	v_mfma_f32_16x16x32_bf16 v[28:31], v[140:143], v[192:195], v[28:31]
	v_mfma_f32_16x16x32_bf16 v[24:27], v[144:147], v[192:195], v[24:27]
	v_mfma_f32_16x16x32_bf16 v[20:23], v[148:151], v[192:195], v[20:23]
	v_mfma_f32_16x16x32_bf16 v[16:19], v[152:155], v[192:195], v[16:19]
	global_load_lds_dwordx4 v[206:207], off
	s_waitcnt lgkmcnt(1)
	v_mfma_f32_16x16x32_bf16 v[12:15], v[140:143], v[156:159], v[12:15]
	v_mfma_f32_16x16x32_bf16 v[8:11], v[144:147], v[156:159], v[8:11]
	v_mfma_f32_16x16x32_bf16 v[4:7], v[148:151], v[156:159], v[4:7]
	v_mfma_f32_16x16x32_bf16 v[0:3], v[152:155], v[156:159], v[0:3]
	s_waitcnt lgkmcnt(0)
	v_mfma_f32_16x16x32_bf16 v[76:79], v[140:143], v[188:191], v[76:79]
	v_mfma_f32_16x16x32_bf16 v[80:83], v[144:147], v[188:191], v[80:83]
	v_mfma_f32_16x16x32_bf16 v[88:91], v[148:151], v[188:191], v[88:91]
	v_mfma_f32_16x16x32_bf16 v[92:95], v[152:155], v[188:191], v[92:95]
	s_setprio 0
	s_add_i32 s12, s10, 1
	s_cmp_lg_u32 s10, 2
	s_cselect_b32 s10, s12, 0
	s_add_i32 s11, s11, 1
	s_cmp_eq_u32 s11, 32
	s_cbranch_scc0 .LBB1_56
	s_cmpk_lt_i32 s7, 0x80
	v_readlane_b32 s10, v242, 5
	s_waitcnt vmcnt(0)
	s_cselect_b64 s[8:9], -1, 0
	v_readlane_b32 s11, v242, 6
	s_and_b64 s[8:9], s[10:11], s[8:9]
	s_mov_b64 s[42:43], -1
	s_and_b64 vcc, exec, s[8:9]
	v_cvt_pk_bf16_f32 v124, v124, v125
	v_cvt_pk_bf16_f32 v125, v126, v127
	v_cvt_pk_bf16_f32 v120, v120, v121
	v_cvt_pk_bf16_f32 v121, v122, v123
	v_cvt_pk_bf16_f32 v116, v116, v117
	v_cvt_pk_bf16_f32 v117, v118, v119
	v_cvt_pk_bf16_f32 v112, v112, v113
	v_cvt_pk_bf16_f32 v113, v114, v115
	v_cvt_pk_bf16_f32 v108, v108, v109
	v_cvt_pk_bf16_f32 v109, v110, v111
	v_cvt_pk_bf16_f32 v104, v104, v105
	v_cvt_pk_bf16_f32 v105, v106, v107
	v_cvt_pk_bf16_f32 v100, v100, v101
	v_cvt_pk_bf16_f32 v101, v102, v103
	v_cvt_pk_bf16_f32 v96, v96, v97
	v_cvt_pk_bf16_f32 v97, v98, v99
	v_cvt_pk_bf16_f32 v84, v84, v85
	v_cvt_pk_bf16_f32 v85, v86, v87
	v_cvt_pk_bf16_f32 v72, v72, v73
	v_cvt_pk_bf16_f32 v73, v74, v75
	v_cvt_pk_bf16_f32 v68, v68, v69
	v_cvt_pk_bf16_f32 v69, v70, v71
	v_cvt_pk_bf16_f32 v64, v64, v65
	v_cvt_pk_bf16_f32 v65, v66, v67
	v_cvt_pk_bf16_f32 v60, v60, v61
	v_cvt_pk_bf16_f32 v61, v62, v63
	v_cvt_pk_bf16_f32 v56, v56, v57
	v_cvt_pk_bf16_f32 v57, v58, v59
	v_cvt_pk_bf16_f32 v52, v52, v53
	v_cvt_pk_bf16_f32 v53, v54, v55
	v_cvt_pk_bf16_f32 v48, v48, v49
	v_cvt_pk_bf16_f32 v49, v50, v51
	v_cvt_pk_bf16_f32 v44, v44, v45
	v_cvt_pk_bf16_f32 v45, v46, v47
	v_cvt_pk_bf16_f32 v40, v40, v41
	v_cvt_pk_bf16_f32 v41, v42, v43
	v_cvt_pk_bf16_f32 v36, v36, v37
	v_cvt_pk_bf16_f32 v37, v38, v39
	v_cvt_pk_bf16_f32 v32, v32, v33
	v_cvt_pk_bf16_f32 v33, v34, v35
	v_cvt_pk_bf16_f32 v28, v28, v29
	v_cvt_pk_bf16_f32 v29, v30, v31
	v_cvt_pk_bf16_f32 v24, v24, v25
	v_cvt_pk_bf16_f32 v25, v26, v27
	v_cvt_pk_bf16_f32 v20, v20, v21
	v_cvt_pk_bf16_f32 v21, v22, v23
	v_cvt_pk_bf16_f32 v16, v16, v17
	v_cvt_pk_bf16_f32 v17, v18, v19
	v_cvt_pk_bf16_f32 v12, v12, v13
	v_cvt_pk_bf16_f32 v13, v14, v15
	v_cvt_pk_bf16_f32 v14, v8, v9
	v_cvt_pk_bf16_f32 v15, v10, v11
	v_cvt_pk_bf16_f32 v8, v4, v5
	v_cvt_pk_bf16_f32 v9, v6, v7
	v_cvt_pk_bf16_f32 v10, v0, v1
	v_cvt_pk_bf16_f32 v11, v2, v3
	v_cvt_pk_bf16_f32 v2, v76, v77
	v_cvt_pk_bf16_f32 v3, v78, v79
	v_cvt_pk_bf16_f32 v6, v80, v81
	v_cvt_pk_bf16_f32 v7, v82, v83
	v_cvt_pk_bf16_f32 v0, v88, v89
	v_cvt_pk_bf16_f32 v1, v90, v91
	v_cvt_pk_bf16_f32 v4, v92, v93
	v_cvt_pk_bf16_f32 v5, v94, v95
	s_waitcnt vmcnt(0)
	s_barrier
	s_cbranch_vccnz .LBB1_59
	s_load_dwordx16 s[64:79], s[0:1], 0x140
	v_or_b32_e32 v18, s4, v135
	v_add_u32_e32 v18, s6, v18
	v_lshl_or_b32 v19, v136, 2, s40
	v_or_b32_e32 v22, s5, v19
	v_ashrrev_i32_e32 v19, 31, v18
	v_lshlrev_b64 v[26:27], 12, v[18:19]
	v_ashrrev_i32_e32 v23, 31, v22
	s_waitcnt lgkmcnt(0)
	v_lshl_add_u64 v[26:27], s[76:77], 0, v[26:27]
	v_lshlrev_b64 v[22:23], 1, v[22:23]
	v_lshl_add_u64 v[26:27], v[26:27], 0, v[22:23]
	global_store_dwordx2 v[26:27], v[124:125], off
	global_store_dwordx2 v[26:27], v[120:121], off offset:32
	global_store_dwordx2 v[26:27], v[116:117], off offset:64
	global_store_dwordx2 v[26:27], v[112:113], off offset:96
	v_or_b32_e32 v26, 16, v18
	v_ashrrev_i32_e32 v27, 31, v26
	v_lshlrev_b64 v[26:27], 12, v[26:27]
	v_lshl_add_u64 v[26:27], s[76:77], 0, v[26:27]
	v_lshl_add_u64 v[26:27], v[26:27], 0, v[22:23]
	global_store_dwordx2 v[26:27], v[108:109], off
	global_store_dwordx2 v[26:27], v[104:105], off offset:32
	global_store_dwordx2 v[26:27], v[100:101], off offset:64
	global_store_dwordx2 v[26:27], v[96:97], off offset:96
	v_or_b32_e32 v26, 32, v18
	v_ashrrev_i32_e32 v27, 31, v26
	v_lshlrev_b64 v[26:27], 12, v[26:27]
	v_lshl_add_u64 v[26:27], s[76:77], 0, v[26:27]
	v_lshl_add_u64 v[26:27], v[26:27], 0, v[22:23]
	global_store_dwordx2 v[26:27], v[84:85], off
	global_store_dwordx2 v[26:27], v[72:73], off offset:32
	global_store_dwordx2 v[26:27], v[68:69], off offset:64
	global_store_dwordx2 v[26:27], v[64:65], off offset:96
	v_or_b32_e32 v26, 48, v18
	v_ashrrev_i32_e32 v27, 31, v26
	v_lshlrev_b64 v[26:27], 12, v[26:27]
	v_lshl_add_u64 v[26:27], s[76:77], 0, v[26:27]
	v_lshl_add_u64 v[26:27], v[26:27], 0, v[22:23]
	global_store_dwordx2 v[26:27], v[60:61], off
	global_store_dwordx2 v[26:27], v[56:57], off offset:32
	global_store_dwordx2 v[26:27], v[52:53], off offset:64
	global_store_dwordx2 v[26:27], v[48:49], off offset:96
	v_or_b32_e32 v26, 64, v18
	v_ashrrev_i32_e32 v27, 31, v26
	v_lshlrev_b64 v[26:27], 12, v[26:27]
	v_lshl_add_u64 v[26:27], s[76:77], 0, v[26:27]
	v_lshl_add_u64 v[26:27], v[26:27], 0, v[22:23]
	global_store_dwordx2 v[26:27], v[44:45], off
	global_store_dwordx2 v[26:27], v[40:41], off offset:32
	global_store_dwordx2 v[26:27], v[36:37], off offset:64
	global_store_dwordx2 v[26:27], v[32:33], off offset:96
	v_or_b32_e32 v26, 0x50, v18
	v_ashrrev_i32_e32 v27, 31, v26
	v_lshlrev_b64 v[26:27], 12, v[26:27]
	v_lshl_add_u64 v[26:27], s[76:77], 0, v[26:27]
	v_lshl_add_u64 v[26:27], v[26:27], 0, v[22:23]
	global_store_dwordx2 v[26:27], v[28:29], off
	global_store_dwordx2 v[26:27], v[24:25], off offset:32
	global_store_dwordx2 v[26:27], v[20:21], off offset:64
	global_store_dwordx2 v[26:27], v[16:17], off offset:96
	v_or_b32_e32 v26, 0x60, v18
	v_ashrrev_i32_e32 v27, 31, v26
	v_lshlrev_b64 v[26:27], 12, v[26:27]
	v_lshl_add_u64 v[26:27], s[76:77], 0, v[26:27]
	v_or_b32_e32 v18, 0x70, v18
	v_lshl_add_u64 v[26:27], v[26:27], 0, v[22:23]
	v_ashrrev_i32_e32 v19, 31, v18
	global_store_dwordx2 v[26:27], v[12:13], off
	global_store_dwordx2 v[26:27], v[14:15], off offset:32
	global_store_dwordx2 v[26:27], v[8:9], off offset:64
	global_store_dwordx2 v[26:27], v[10:11], off offset:96
	v_lshlrev_b64 v[18:19], 12, v[18:19]
	v_lshl_add_u64 v[18:19], s[76:77], 0, v[18:19]
	s_load_dwordx16 s[64:79], s[0:1], 0x100
	v_lshl_add_u64 v[18:19], v[18:19], 0, v[22:23]
	s_mov_b64 s[42:43], 0
	global_store_dwordx2 v[18:19], v[2:3], off
	global_store_dwordx2 v[18:19], v[6:7], off offset:32
	global_store_dwordx2 v[18:19], v[0:1], off offset:64
	global_store_dwordx2 v[18:19], v[4:5], off offset:96

.LBB1_1180:
	s_mul_i32 s13, s11, 0x6000
	s_add_i32 s14, s13, 0xffffa000
	s_cmp_lg_u32 s11, 0
	s_cselect_b32 s14, s14, 0xc000
	s_min_u32 s15, s12, 29
	s_lshl_b32 s96, s15, 6
	s_add_i32 s14, s14, 16
	v_lshl_add_u64 v[136:137], v[130:131], 0, s[96:97]
	s_add_i32 s15, s14, s9
	v_lshl_add_u64 v[196:197], v[136:137], 0, s[62:63]
	v_lshl_add_u64 v[198:199], v[136:137], 0, s[60:61]
	v_lshl_add_u64 v[200:201], v[136:137], 0, s[16:17]
	v_lshl_add_u64 v[202:203], v[136:137], 0, s[24:25]
	s_add_i32 s14, s14, s10
	s_add_i32 s13, s13, 16
	v_lshl_add_u64 v[136:137], v[132:133], 0, s[96:97]
	v_lshl_add_u64 v[204:205], v[136:137], 0, s[62:63]
	v_lshl_add_u64 v[206:207], v[136:137], 0, s[60:61]
	s_waitcnt vmcnt(6)
	s_barrier
	v_add3_u32 v136, s13, v135, v134
	ds_read_b128 v[142:145], v136 offset:16384
	ds_read_b128 v[146:149], v136 offset:17408
	ds_read_b128 v[150:153], v136 offset:18432
	ds_read_b128 v[154:157], v136 offset:19456
	s_setprio 1
	v_add3_u32 v136, s13, v128, v134
	ds_read_b128 v[158:161], v136
	ds_read_b128 v[188:191], v136 offset:1024
	ds_read_b128 v[192:195], v136 offset:2048
	s_waitcnt lgkmcnt(2)
	s_mov_b32 m0, s15
	v_mfma_f32_16x16x32_bf16 v[124:127], v[142:145], v[158:161], v[124:127]
	v_mfma_f32_16x16x32_bf16 v[120:123], v[146:149], v[158:161], v[120:123]
	v_mfma_f32_16x16x32_bf16 v[116:119], v[150:153], v[158:161], v[116:119]
	v_mfma_f32_16x16x32_bf16 v[112:115], v[154:157], v[158:161], v[112:115]
	ds_read_b128 v[158:161], v136 offset:3072
	global_load_lds_dwordx4 v[196:197], off
	s_waitcnt lgkmcnt(2)
	s_add_i32 m0, s15, 0x400
	v_mfma_f32_16x16x32_bf16 v[108:111], v[142:145], v[188:191], v[108:111]
	v_mfma_f32_16x16x32_bf16 v[104:107], v[146:149], v[188:191], v[104:107]
	v_mfma_f32_16x16x32_bf16 v[100:103], v[150:153], v[188:191], v[100:103]
	v_mfma_f32_16x16x32_bf16 v[96:99], v[154:157], v[188:191], v[96:99]
	ds_read_b128 v[188:191], v136 offset:4096
	global_load_lds_dwordx4 v[198:199], off
	s_waitcnt lgkmcnt(2)
	s_add_i32 m0, s15, 0x800
	v_mfma_f32_16x16x32_bf16 v[92:95], v[142:145], v[192:195], v[92:95]
	v_mfma_f32_16x16x32_bf16 v[88:91], v[146:149], v[192:195], v[88:91]
	v_mfma_f32_16x16x32_bf16 v[84:87], v[150:153], v[192:195], v[84:87]
	v_mfma_f32_16x16x32_bf16 v[80:83], v[154:157], v[192:195], v[80:83]
	ds_read_b128 v[192:195], v136 offset:5120
	global_load_lds_dwordx4 v[200:201], off
	s_waitcnt lgkmcnt(2)
	s_add_i32 m0, s15, 0xc00
	v_mfma_f32_16x16x32_bf16 v[76:79], v[142:145], v[158:161], v[76:79]
	v_mfma_f32_16x16x32_bf16 v[72:75], v[146:149], v[158:161], v[72:75]
	v_mfma_f32_16x16x32_bf16 v[68:71], v[150:153], v[158:161], v[68:71]
	v_mfma_f32_16x16x32_bf16 v[48:51], v[154:157], v[158:161], v[48:51]
	ds_read_b128 v[158:161], v136 offset:6144
	global_load_lds_dwordx4 v[202:203], off
	s_waitcnt lgkmcnt(2)
	s_add_i32 m0, s14, 0x4000
	v_mfma_f32_16x16x32_bf16 v[44:47], v[142:145], v[188:191], v[44:47]
	v_mfma_f32_16x16x32_bf16 v[40:43], v[146:149], v[188:191], v[40:43]
	v_mfma_f32_16x16x32_bf16 v[36:39], v[150:153], v[188:191], v[36:39]
	v_mfma_f32_16x16x32_bf16 v[32:35], v[154:157], v[188:191], v[32:35]
	ds_read_b128 v[188:191], v136 offset:7168
	global_load_lds_dwordx4 v[204:205], off
	s_waitcnt lgkmcnt(2)
	s_add_i32 m0, s14, 0x4400
	v_mfma_f32_16x16x32_bf16 v[28:31], v[142:145], v[192:195], v[28:31]
	v_mfma_f32_16x16x32_bf16 v[24:27], v[146:149], v[192:195], v[24:27]
	v_mfma_f32_16x16x32_bf16 v[20:23], v[150:153], v[192:195], v[20:23]
	v_mfma_f32_16x16x32_bf16 v[16:19], v[154:157], v[192:195], v[16:19]
	global_load_lds_dwordx4 v[206:207], off
	s_waitcnt lgkmcnt(1)
	v_mfma_f32_16x16x32_bf16 v[12:15], v[142:145], v[158:161], v[12:15]
	v_mfma_f32_16x16x32_bf16 v[8:11], v[146:149], v[158:161], v[8:11]
	v_mfma_f32_16x16x32_bf16 v[4:7], v[150:153], v[158:161], v[4:7]
	v_mfma_f32_16x16x32_bf16 v[0:3], v[154:157], v[158:161], v[0:3]
	s_waitcnt lgkmcnt(0)
	v_mfma_f32_16x16x32_bf16 v[60:63], v[142:145], v[188:191], v[60:63]
	v_mfma_f32_16x16x32_bf16 v[64:67], v[146:149], v[188:191], v[64:67]
	v_mfma_f32_16x16x32_bf16 v[52:55], v[150:153], v[188:191], v[52:55]
	v_mfma_f32_16x16x32_bf16 v[56:59], v[154:157], v[188:191], v[56:59]
	s_setprio 0
	s_add_i32 s13, s11, 1
	s_cmp_lg_u32 s11, 2
	s_cselect_b32 s11, s13, 0
	s_add_i32 s12, s12, 1
	s_cmp_eq_u32 s12, 32
	s_cbranch_scc0 .LBB1_1180
	s_waitcnt vmcnt(0)
	s_waitcnt vmcnt(0)
	s_barrier
	s_load_dwordx8 s[80:87], s[0:1], 0x180
	s_cmp_lt_i32 s4, 64
	v_readlane_b32 s12, v242, 9
	s_cselect_b64 s[10:11], -1, 0
	v_readlane_b32 s13, v242, 10
	s_and_b64 s[10:11], s[12:13], s[10:11]
	s_mov_b64 s[38:39], -1
	s_and_b64 vcc, exec, s[10:11]
	s_movk_i32 s12, 0x2020
	s_cbranch_vccnz .LBB1_1291
	v_or_b32_e32 v128, s6, v139
	v_add_u32_e32 v132, s8, v128
	v_lshl_or_b32 v128, v140, 2, s30
	v_or_b32_e32 v130, s7, v128
	v_lshlrev_b32_e32 v134, 5, v132
	s_movk_i32 s8, 0x1fff
	v_ashrrev_i32_e32 v135, 31, v134
	v_cmp_lt_i32_e32 vcc, s8, v130
	s_and_saveexec_b64 s[8:9], vcc
	s_xor_b64 s[40:41], exec, s[8:9]
	s_cbranch_execz .LBB1_1186
	v_cmp_gt_u32_e64 s[38:39], s12, v130
	s_and_saveexec_b64 s[42:43], s[38:39]
	s_cbranch_execz .LBB1_1185
	v_add_u32_e32 v128, 0xffffe000, v130
	v_lshl_add_u64 v[136:137], v[134:135], 2, s[78:79]
	v_lshlrev_b64 v[142:143], 2, v[128:129]
	v_lshl_add_u64 v[136:137], v[136:137], 0, v[142:143]
	v_lshl_add_u64 v[142:143], s[22:23], 0, v[142:143]
	global_load_dwordx4 v[142:145], v[142:143], off
	s_waitcnt vmcnt(0)
	v_pk_add_f32 v[144:145], v[126:127], v[144:145]
	v_pk_add_f32 v[142:143], v[124:125], v[142:143]
	global_store_dwordx4 v[136:137], v[142:145], off
